# last-phase second pass: 8 row statistics and 4 gain quads loaded once up front instead of 40 serialised reload+drain steps per wave
# baseline (speedup 1.0000x reference)
;     __device__ __forceinline__ void fused(f32x4 (&acc)[2][2][4][2], const Unit& u, int wr, int wc, int fr, int fq, PG8_LAS unsigned char* lds, int wid, int lane) const {
;     ...
; #pragma unroll
;         for (int ai = 0; ai < 2; ++ai)
; #pragma unroll
;             for (int m = 0; m < 4; ++m) { const int row = row0 + ai * HALF + m * 16; const size_t off = (size_t)row * 1024 + col0;
;                 const float rs = rsqrtf(__hip_atomic_load(ssq + row, __ATOMIC_RELAXED, __HIP_MEMORY_SCOPE_AGENT) * (1.f / 1024.f) + RMS_EPS);
; #pragma unroll
;                 for (int bj = 0; bj < 2; ++bj)
; #pragma unroll
;                     for (int n = 0; n < 2; ++n) { const f32x4 g = *(const f32x4*)(gain + col0 + bj * HALF + n * 4); *(f32x4*)(out + off + bj * HALF + n * 4) = acc[ai][bj][m][n] * rs * g; } }
.LBB0_1467:
	s_waitcnt vmcnt(0) lgkmcnt(0)
	s_barrier
	s_waitcnt lgkmcnt(0)
	v_lshl_add_u64 v[148:149], v[128:129], 2, s[2:3]
	global_load_dword v160, v[148:149], off sc1
	global_load_dword v161, v[148:149], off offset:64 sc1
	global_load_dword v162, v[148:149], off offset:128 sc1
	global_load_dword v163, v[148:149], off offset:192 sc1
	global_load_dword v164, v[148:149], off offset:512 sc1
	global_load_dword v165, v[148:149], off offset:576 sc1
	global_load_dword v166, v[148:149], off offset:640 sc1
	global_load_dword v167, v[148:149], off offset:704 sc1
	v_lshlrev_b64 v[146:147], 2, v[130:131]
	v_lshl_add_u64 v[130:131], s[8:9], 0, v[146:147]
	global_load_dwordx4 v[168:171], v[130:131], off
	global_load_dwordx4 v[172:175], v[130:131], off offset:16
	global_load_dwordx4 v[176:179], v[130:131], off offset:512
	global_load_dwordx4 v[180:183], v[130:131], off offset:528
	v_mov_b32_e32 v150, 0x358637bd
	s_mov_b32 s0, 0x800000
	v_lshlrev_b64 v[128:129], 12, v[128:129]
	v_lshl_add_u64 v[128:129], s[10:11], 0, v[128:129]
	s_waitcnt vmcnt(0)
	v_fmamk_f32 v151, v160, 0x3a800000, v150
	v_mul_f32_e32 v156, 0x4b800000, v151
	v_cmp_gt_f32_e32 vcc, s0, v151
	s_nop 1
	v_cndmask_b32_e32 v151, v151, v156, vcc
	v_rsq_f32_e32 v151, v151
	v_lshl_add_u64 v[156:157], v[128:129], 0, v[146:147]
	v_mul_f32_e32 v128, 0x45800000, v151
	v_cndmask_b32_e32 v158, v151, v128, vcc
	v_pk_mul_f32 v[132:133], v[132:133], v[158:159] op_sel_hi:[1,0]
	v_pk_mul_f32 v[126:127], v[126:127], v[158:159] op_sel_hi:[1,0]
	v_pk_mul_f32 v[122:123], v[122:123], v[158:159] op_sel_hi:[1,0]
	v_pk_mul_f32 v[128:129], v[170:171], v[126:127]
	v_pk_mul_f32 v[126:127], v[168:169], v[132:133]
	global_store_dwordx4 v[156:157], v[126:129], off
	v_pk_mul_f32 v[120:121], v[120:121], v[158:159] op_sel_hi:[1,0]
	v_pk_mul_f32 v[118:119], v[118:119], v[158:159] op_sel_hi:[1,0]
	v_pk_mul_f32 v[116:117], v[116:117], v[158:159] op_sel_hi:[1,0]
	v_pk_mul_f32 v[114:115], v[114:115], v[158:159] op_sel_hi:[1,0]
	v_pk_mul_f32 v[112:113], v[112:113], v[158:159] op_sel_hi:[1,0]
	v_pk_mul_f32 v[120:121], v[172:173], v[120:121]
	v_pk_mul_f32 v[122:123], v[174:175], v[122:123]
	global_store_dwordx4 v[156:157], v[120:123], off offset:16
	v_pk_mul_f32 v[116:117], v[176:177], v[116:117]
	v_pk_mul_f32 v[118:119], v[178:179], v[118:119]
	global_store_dwordx4 v[156:157], v[116:119], off offset:512
	v_lshl_add_u64 v[120:121], v[124:125], 2, s[2:3]
	v_pk_mul_f32 v[112:113], v[180:181], v[112:113]
	v_pk_mul_f32 v[114:115], v[182:183], v[114:115]
	global_store_dwordx4 v[156:157], v[112:115], off offset:528
	s_nop 0
	v_fmamk_f32 v116, v161, 0x3a800000, v150
	v_mul_f32_e32 v117, 0x4b800000, v116
	v_cmp_gt_f32_e32 vcc, s0, v116
	s_nop 1
	v_cndmask_b32_e32 v116, v116, v117, vcc
	v_rsq_f32_e32 v118, v116
	v_lshlrev_b64 v[116:117], 12, v[124:125]
	v_lshl_add_u64 v[116:117], s[10:11], 0, v[116:117]
	v_lshl_add_u64 v[116:117], v[116:117], 0, v[146:147]
	v_mul_f32_e32 v119, 0x45800000, v118
	v_cndmask_b32_e32 v118, v118, v119, vcc
	v_pk_mul_f32 v[120:121], v[134:135], v[118:119] op_sel_hi:[1,0]
	v_pk_mul_f32 v[110:111], v[110:111], v[118:119] op_sel_hi:[1,0]
	v_pk_mul_f32 v[112:113], v[168:169], v[120:121]
	v_pk_mul_f32 v[114:115], v[170:171], v[110:111]
	global_store_dwordx4 v[116:117], v[112:115], off
	v_pk_mul_f32 v[106:107], v[106:107], v[118:119] op_sel_hi:[1,0]
	v_pk_mul_f32 v[104:105], v[104:105], v[118:119] op_sel_hi:[1,0]
	v_pk_mul_f32 v[102:103], v[102:103], v[118:119] op_sel_hi:[1,0]
	v_pk_mul_f32 v[100:101], v[100:101], v[118:119] op_sel_hi:[1,0]
	v_pk_mul_f32 v[98:99], v[98:99], v[118:119] op_sel_hi:[1,0]
	v_pk_mul_f32 v[96:97], v[96:97], v[118:119] op_sel_hi:[1,0]
	v_pk_mul_f32 v[104:105], v[172:173], v[104:105]
	v_pk_mul_f32 v[106:107], v[174:175], v[106:107]
	global_store_dwordx4 v[116:117], v[104:107], off offset:16
	v_pk_mul_f32 v[100:101], v[176:177], v[100:101]
	v_pk_mul_f32 v[102:103], v[178:179], v[102:103]
	global_store_dwordx4 v[116:117], v[100:103], off offset:512
	v_lshl_add_u64 v[104:105], v[108:109], 2, s[2:3]
	v_pk_mul_f32 v[96:97], v[180:181], v[96:97]
	v_pk_mul_f32 v[98:99], v[182:183], v[98:99]
	global_store_dwordx4 v[116:117], v[96:99], off offset:528
	s_nop 0
	v_fmamk_f32 v100, v162, 0x3a800000, v150
	v_mul_f32_e32 v101, 0x4b800000, v100
	v_cmp_gt_f32_e32 vcc, s0, v100
	s_nop 1
	v_cndmask_b32_e32 v100, v100, v101, vcc
	v_rsq_f32_e32 v102, v100
	v_lshlrev_b64 v[100:101], 12, v[108:109]
	v_lshl_add_u64 v[100:101], s[10:11], 0, v[100:101]
	v_lshl_add_u64 v[100:101], v[100:101], 0, v[146:147]
	v_mul_f32_e32 v103, 0x45800000, v102
	v_cndmask_b32_e32 v102, v102, v103, vcc
	v_pk_mul_f32 v[104:105], v[136:137], v[102:103] op_sel_hi:[1,0]
	v_pk_mul_f32 v[94:95], v[94:95], v[102:103] op_sel_hi:[1,0]
	v_pk_mul_f32 v[96:97], v[168:169], v[104:105]
	v_pk_mul_f32 v[98:99], v[170:171], v[94:95]
	global_store_dwordx4 v[100:101], v[96:99], off
	v_pk_mul_f32 v[90:91], v[90:91], v[102:103] op_sel_hi:[1,0]
	v_pk_mul_f32 v[88:89], v[88:89], v[102:103] op_sel_hi:[1,0]
	v_pk_mul_f32 v[86:87], v[86:87], v[102:103] op_sel_hi:[1,0]
	v_pk_mul_f32 v[84:85], v[84:85], v[102:103] op_sel_hi:[1,0]
	v_pk_mul_f32 v[82:83], v[82:83], v[102:103] op_sel_hi:[1,0]
	v_pk_mul_f32 v[80:81], v[80:81], v[102:103] op_sel_hi:[1,0]
	v_pk_mul_f32 v[88:89], v[172:173], v[88:89]
	v_pk_mul_f32 v[90:91], v[174:175], v[90:91]
	global_store_dwordx4 v[100:101], v[88:91], off offset:16
	v_pk_mul_f32 v[84:85], v[176:177], v[84:85]
	v_pk_mul_f32 v[86:87], v[178:179], v[86:87]
	global_store_dwordx4 v[100:101], v[84:87], off offset:512
	v_lshl_add_u64 v[88:89], v[92:93], 2, s[2:3]
	v_pk_mul_f32 v[80:81], v[180:181], v[80:81]
	v_pk_mul_f32 v[82:83], v[182:183], v[82:83]
;     __device__ __forceinline__ void fused(f32x4 (&acc)[2][2][4][2], const Unit& u, int wr, int wc, int fr, int fq, PG8_LAS unsigned char* lds, int wid, int lane) const {
;     ...
; #pragma unroll
;         for (int ai = 0; ai < 2; ++ai)
; #pragma unroll
;             for (int m = 0; m < 4; ++m) { const int row = row0 + ai * HALF + m * 16; const size_t off = (size_t)row * 1024 + col0;
;                 const float rs = rsqrtf(__hip_atomic_load(ssq + row, __ATOMIC_RELAXED, __HIP_MEMORY_SCOPE_AGENT) * (1.f / 1024.f) + RMS_EPS);
; #pragma unroll
;                 for (int bj = 0; bj < 2; ++bj)
; #pragma unroll
;                     for (int n = 0; n < 2; ++n) { const f32x4 g = *(const f32x4*)(gain + col0 + bj * HALF + n * 4); *(f32x4*)(out + off + bj * HALF + n * 4) = acc[ai][bj][m][n] * rs * g; } }
	global_store_dwordx4 v[100:101], v[80:83], off offset:528
	s_nop 0
	v_fmamk_f32 v84, v163, 0x3a800000, v150
	v_mul_f32_e32 v85, 0x4b800000, v84
	v_cmp_gt_f32_e32 vcc, s0, v84
	s_nop 1
	v_cndmask_b32_e32 v84, v84, v85, vcc
	v_rsq_f32_e32 v86, v84
	v_lshlrev_b64 v[84:85], 12, v[92:93]
	v_lshl_add_u64 v[84:85], s[10:11], 0, v[84:85]
	v_lshl_add_u64 v[84:85], v[84:85], 0, v[146:147]
	v_mul_f32_e32 v87, 0x45800000, v86
	v_cndmask_b32_e32 v86, v86, v87, vcc
	v_pk_mul_f32 v[88:89], v[138:139], v[86:87] op_sel_hi:[1,0]
	v_pk_mul_f32 v[78:79], v[78:79], v[86:87] op_sel_hi:[1,0]
	v_pk_mul_f32 v[80:81], v[168:169], v[88:89]
	v_pk_mul_f32 v[82:83], v[170:171], v[78:79]
	global_store_dwordx4 v[84:85], v[80:83], off
	v_pk_mul_f32 v[74:75], v[74:75], v[86:87] op_sel_hi:[1,0]
	v_pk_mul_f32 v[72:73], v[72:73], v[86:87] op_sel_hi:[1,0]
	v_pk_mul_f32 v[70:71], v[70:71], v[86:87] op_sel_hi:[1,0]
	v_pk_mul_f32 v[68:69], v[68:69], v[86:87] op_sel_hi:[1,0]
	v_pk_mul_f32 v[66:67], v[66:67], v[86:87] op_sel_hi:[1,0]
	v_pk_mul_f32 v[64:65], v[64:65], v[86:87] op_sel_hi:[1,0]
	v_pk_mul_f32 v[72:73], v[172:173], v[72:73]
	v_pk_mul_f32 v[74:75], v[174:175], v[74:75]
	global_store_dwordx4 v[84:85], v[72:75], off offset:16
	v_pk_mul_f32 v[68:69], v[176:177], v[68:69]
	v_pk_mul_f32 v[70:71], v[178:179], v[70:71]
	global_store_dwordx4 v[84:85], v[68:71], off offset:512
	v_pk_mul_f32 v[64:65], v[180:181], v[64:65]
	v_pk_mul_f32 v[66:67], v[182:183], v[66:67]
	global_store_dwordx4 v[84:85], v[64:67], off offset:528
	s_nop 0
	v_fmamk_f32 v68, v164, 0x3a800000, v150
	v_mul_f32_e32 v69, 0x4b800000, v68
	v_cmp_gt_f32_e32 vcc, s0, v68
	s_nop 1
	v_cndmask_b32_e32 v68, v68, v69, vcc
	v_rsq_f32_e32 v70, v68
	v_lshlrev_b64 v[68:69], 12, v[76:77]
	v_lshl_add_u64 v[68:69], s[10:11], 0, v[68:69]
	v_lshl_add_u64 v[68:69], v[68:69], 0, v[146:147]
	v_mul_f32_e32 v71, 0x45800000, v70
	v_cndmask_b32_e32 v70, v70, v71, vcc
	v_pk_mul_f32 v[72:73], v[140:141], v[70:71] op_sel_hi:[1,0]
	v_pk_mul_f32 v[62:63], v[62:63], v[70:71] op_sel_hi:[1,0]
	v_pk_mul_f32 v[64:65], v[168:169], v[72:73]
	v_pk_mul_f32 v[66:67], v[170:171], v[62:63]
	global_store_dwordx4 v[68:69], v[64:67], off
	v_pk_mul_f32 v[58:59], v[58:59], v[70:71] op_sel_hi:[1,0]
	v_pk_mul_f32 v[56:57], v[56:57], v[70:71] op_sel_hi:[1,0]
	v_pk_mul_f32 v[54:55], v[54:55], v[70:71] op_sel_hi:[1,0]
	v_pk_mul_f32 v[52:53], v[52:53], v[70:71] op_sel_hi:[1,0]
	v_pk_mul_f32 v[50:51], v[50:51], v[70:71] op_sel_hi:[1,0]
	v_pk_mul_f32 v[48:49], v[48:49], v[70:71] op_sel_hi:[1,0]
	v_pk_mul_f32 v[56:57], v[172:173], v[56:57]
	v_pk_mul_f32 v[58:59], v[174:175], v[58:59]
	global_store_dwordx4 v[68:69], v[56:59], off offset:16
	v_pk_mul_f32 v[52:53], v[176:177], v[52:53]
	v_pk_mul_f32 v[54:55], v[178:179], v[54:55]
	global_store_dwordx4 v[68:69], v[52:55], off offset:512
	v_pk_mul_f32 v[48:49], v[180:181], v[48:49]
	v_pk_mul_f32 v[50:51], v[182:183], v[50:51]
	global_store_dwordx4 v[68:69], v[48:51], off offset:528
	s_nop 0
	v_fmamk_f32 v52, v165, 0x3a800000, v150
	v_mul_f32_e32 v53, 0x4b800000, v52
	v_cmp_gt_f32_e32 vcc, s0, v52
	s_nop 1
	v_cndmask_b32_e32 v52, v52, v53, vcc
	v_rsq_f32_e32 v54, v52
	v_lshlrev_b64 v[52:53], 12, v[60:61]
	v_lshl_add_u64 v[52:53], s[10:11], 0, v[52:53]
	v_lshl_add_u64 v[52:53], v[52:53], 0, v[146:147]
	v_mul_f32_e32 v55, 0x45800000, v54
	v_cndmask_b32_e32 v54, v54, v55, vcc
	v_pk_mul_f32 v[56:57], v[142:143], v[54:55] op_sel_hi:[1,0]
	v_pk_mul_f32 v[46:47], v[46:47], v[54:55] op_sel_hi:[1,0]
	v_pk_mul_f32 v[48:49], v[168:169], v[56:57]
	v_pk_mul_f32 v[50:51], v[170:171], v[46:47]
	global_store_dwordx4 v[52:53], v[48:51], off
;     __device__ __forceinline__ void fused(f32x4 (&acc)[2][2][4][2], const Unit& u, int wr, int wc, int fr, int fq, PG8_LAS unsigned char* lds, int wid, int lane) const {
;     ...
; #pragma unroll
;         for (int ai = 0; ai < 2; ++ai)
; #pragma unroll
;             for (int m = 0; m < 4; ++m) { const int row = row0 + ai * HALF + m * 16; const size_t off = (size_t)row * 1024 + col0;
;                 const float rs = rsqrtf(__hip_atomic_load(ssq + row, __ATOMIC_RELAXED, __HIP_MEMORY_SCOPE_AGENT) * (1.f / 1024.f) + RMS_EPS);
; #pragma unroll
;                 for (int bj = 0; bj < 2; ++bj)
; #pragma unroll
;                     for (int n = 0; n < 2; ++n) { const f32x4 g = *(const f32x4*)(gain + col0 + bj * HALF + n * 4); *(f32x4*)(out + off + bj * HALF + n * 4) = acc[ai][bj][m][n] * rs * g; } }
	v_pk_mul_f32 v[42:43], v[42:43], v[54:55] op_sel_hi:[1,0]
	v_pk_mul_f32 v[40:41], v[40:41], v[54:55] op_sel_hi:[1,0]
	v_pk_mul_f32 v[38:39], v[38:39], v[54:55] op_sel_hi:[1,0]
	v_pk_mul_f32 v[36:37], v[36:37], v[54:55] op_sel_hi:[1,0]
	v_pk_mul_f32 v[34:35], v[34:35], v[54:55] op_sel_hi:[1,0]
	v_pk_mul_f32 v[32:33], v[32:33], v[54:55] op_sel_hi:[1,0]
	v_pk_mul_f32 v[40:41], v[172:173], v[40:41]
	v_pk_mul_f32 v[42:43], v[174:175], v[42:43]
	global_store_dwordx4 v[52:53], v[40:43], off offset:16
	v_pk_mul_f32 v[36:37], v[176:177], v[36:37]
	v_pk_mul_f32 v[38:39], v[178:179], v[38:39]
	global_store_dwordx4 v[52:53], v[36:39], off offset:512
	v_pk_mul_f32 v[32:33], v[180:181], v[32:33]
	v_pk_mul_f32 v[34:35], v[182:183], v[34:35]
	global_store_dwordx4 v[52:53], v[32:35], off offset:528
	s_nop 0
	v_fmamk_f32 v36, v166, 0x3a800000, v150
	v_mul_f32_e32 v37, 0x4b800000, v36
	v_cmp_gt_f32_e32 vcc, s0, v36
	s_nop 1
	v_cndmask_b32_e32 v36, v36, v37, vcc
	v_rsq_f32_e32 v38, v36
	v_lshlrev_b64 v[36:37], 12, v[44:45]
	v_lshl_add_u64 v[36:37], s[10:11], 0, v[36:37]
	v_lshl_add_u64 v[36:37], v[36:37], 0, v[146:147]
	v_mul_f32_e32 v39, 0x45800000, v38
	v_cndmask_b32_e32 v38, v38, v39, vcc
	v_pk_mul_f32 v[40:41], v[144:145], v[38:39] op_sel_hi:[1,0]
	v_pk_mul_f32 v[30:31], v[30:31], v[38:39] op_sel_hi:[1,0]
	v_pk_mul_f32 v[32:33], v[168:169], v[40:41]
	v_pk_mul_f32 v[34:35], v[170:171], v[30:31]
	global_store_dwordx4 v[36:37], v[32:35], off
	v_pk_mul_f32 v[26:27], v[26:27], v[38:39] op_sel_hi:[1,0]
	v_pk_mul_f32 v[24:25], v[24:25], v[38:39] op_sel_hi:[1,0]
	v_pk_mul_f32 v[22:23], v[22:23], v[38:39] op_sel_hi:[1,0]
	v_pk_mul_f32 v[20:21], v[20:21], v[38:39] op_sel_hi:[1,0]
	v_pk_mul_f32 v[18:19], v[18:19], v[38:39] op_sel_hi:[1,0]
	v_pk_mul_f32 v[16:17], v[16:17], v[38:39] op_sel_hi:[1,0]
	v_pk_mul_f32 v[24:25], v[172:173], v[24:25]
	v_pk_mul_f32 v[26:27], v[174:175], v[26:27]
	global_store_dwordx4 v[36:37], v[24:27], off offset:16
	v_pk_mul_f32 v[20:21], v[176:177], v[20:21]
	v_pk_mul_f32 v[22:23], v[178:179], v[22:23]
	global_store_dwordx4 v[36:37], v[20:23], off offset:512
	v_pk_mul_f32 v[16:17], v[180:181], v[16:17]
	v_pk_mul_f32 v[18:19], v[182:183], v[18:19]
	global_store_dwordx4 v[36:37], v[16:19], off offset:528
	s_nop 0
	v_fmac_f32_e32 v150, 0x3a800000, v167
	v_mul_f32_e32 v20, 0x4b800000, v150
	v_cmp_gt_f32_e32 vcc, s0, v150
	s_nop 1
	v_cndmask_b32_e32 v20, v150, v20, vcc
	v_rsq_f32_e32 v22, v20
	v_lshlrev_b64 v[20:21], 12, v[28:29]
	v_lshl_add_u64 v[20:21], s[10:11], 0, v[20:21]
	v_lshl_add_u64 v[20:21], v[20:21], 0, v[146:147]
	v_mul_f32_e32 v23, 0x45800000, v22
	v_cndmask_b32_e32 v22, v22, v23, vcc
	v_pk_mul_f32 v[12:13], v[12:13], v[22:23] op_sel_hi:[1,0]
	v_pk_mul_f32 v[14:15], v[14:15], v[22:23] op_sel_hi:[1,0]
	v_pk_mul_f32 v[12:13], v[168:169], v[12:13]
	v_pk_mul_f32 v[14:15], v[170:171], v[14:15]
	global_store_dwordx4 v[20:21], v[12:15], off
	v_pk_mul_f32 v[10:11], v[10:11], v[22:23] op_sel_hi:[1,0]
	v_pk_mul_f32 v[8:9], v[8:9], v[22:23] op_sel_hi:[1,0]
	v_pk_mul_f32 v[6:7], v[6:7], v[22:23] op_sel_hi:[1,0]
	v_pk_mul_f32 v[4:5], v[4:5], v[22:23] op_sel_hi:[1,0]
	v_pk_mul_f32 v[2:3], v[2:3], v[22:23] op_sel_hi:[1,0]
	v_pk_mul_f32 v[0:1], v[0:1], v[22:23] op_sel_hi:[1,0]
	v_pk_mul_f32 v[8:9], v[172:173], v[8:9]
	v_pk_mul_f32 v[10:11], v[174:175], v[10:11]
	global_store_dwordx4 v[20:21], v[8:11], off offset:16
	v_pk_mul_f32 v[4:5], v[176:177], v[4:5]
	v_pk_mul_f32 v[6:7], v[178:179], v[6:7]
	global_store_dwordx4 v[20:21], v[4:7], off offset:512
	v_pk_mul_f32 v[0:1], v[180:181], v[0:1]
	v_pk_mul_f32 v[2:3], v[182:183], v[2:3]
	global_store_dwordx4 v[20:21], v[0:3], off offset:528
